# both norm2 row loops hand-written with next-row prefetch (double-buffered registers, scalar addressing)
# speedup vs baseline: 1.0032x; 1.0019x over previous
.LBB0_596:
	s_or_b64 exec, exec, s[4:5]
	s_barrier
	s_mov_b64 s[4:5], exec
	v_readlane_b32 s2, v252, 24
	v_readlane_b32 s3, v252, 25
	s_and_b64 s[2:3], s[4:5], s[2:3]
	s_mov_b64 exec, s[2:3]
	s_cbranch_execz .LBB0_599
	s_waitcnt vmcnt(0)
	v_readlane_b32 s26, v252, 6
	v_readlane_b32 s27, v252, 7
	v_readfirstlane_b32 s16, v152
	s_nop 4
	global_load_dwordx4 v[0:3], v158, s[26:27]
	global_load_dwordx4 v[4:7], v158, s[26:27] offset:1024
	global_load_dwordx4 v[8:11], v158, s[26:27] offset:2048
	global_load_dwordx4 v[12:15], v158, s[26:27] offset:3072
	v_lshrrev_b32_e32 v55, 1, v158
	s_lshl_b32 s17, s16, 12
	s_lshr_b32 s20, s16, 20
	s_add_u32 s18, s92, s17
	s_addc_u32 s19, s93, s20
	global_load_dwordx4 v[16:19], v158, s[18:19]
	global_load_dwordx4 v[20:23], v158, s[18:19] offset:1024
	global_load_dwordx4 v[24:27], v158, s[18:19] offset:2048
	global_load_dwordx4 v[28:31], v158, s[18:19] offset:3072
.Lrms_n0_loop:
	s_add_u32 s21, s16, s34
	s_cmp_lt_u32 s21, 0x10200
	s_cbranch_scc0 .Lrms_n0_skip_a
	s_lshl_b32 s17, s21, 12
	s_lshr_b32 s20, s21, 20
	s_add_u32 s18, s92, s17
	s_addc_u32 s19, s93, s20
	global_load_dwordx4 v[32:35], v158, s[18:19]
	global_load_dwordx4 v[36:39], v158, s[18:19] offset:1024
	global_load_dwordx4 v[40:43], v158, s[18:19] offset:2048
	global_load_dwordx4 v[44:47], v158, s[18:19] offset:3072
	s_waitcnt vmcnt(4)
	s_branch .Lrms_n0_comp_a

.Lrms_n0_comp_a:
	v_pk_mul_f32 v[48:49], v[16:17], v[16:17]
	v_pk_mul_f32 v[50:51], v[18:19], v[18:19]
	v_pk_fma_f32 v[48:49], v[20:21], v[20:21], v[48:49]
	v_pk_fma_f32 v[50:51], v[22:23], v[22:23], v[50:51]
	v_pk_fma_f32 v[48:49], v[24:25], v[24:25], v[48:49]
	v_pk_fma_f32 v[50:51], v[26:27], v[26:27], v[50:51]
	v_pk_fma_f32 v[48:49], v[28:29], v[28:29], v[48:49]
	v_pk_fma_f32 v[50:51], v[30:31], v[30:31], v[50:51]
	s_nop 0
	v_pk_add_f32 v[48:49], v[48:49], v[50:51]
	s_nop 0
	v_add_f32_e32 v52, v48, v49
	s_nop 1
	v_add_f32_dpp v52, v52, v52 quad_perm:[1,0,3,2] row_mask:0xf bank_mask:0xf bound_ctrl:1
	s_nop 1
	v_add_f32_dpp v52, v52, v52 quad_perm:[2,3,0,1] row_mask:0xf bank_mask:0xf bound_ctrl:1
	s_nop 1
	v_add_f32_dpp v52, v52, v52 row_half_mirror row_mask:0xf bank_mask:0xf bound_ctrl:1
	s_nop 1
	v_add_f32_dpp v52, v52, v52 row_mirror row_mask:0xf bank_mask:0xf bound_ctrl:1
	s_nop 1
	v_mov_b32_dpp v53, v52 row_bcast:15 row_mask:0xa bank_mask:0xf
	v_add_f32_e32 v53, v52, v53
	s_nop 1
	v_mov_b32_dpp v54, v53 row_bcast:31 row_mask:0xc bank_mask:0xf
	v_add_f32_e32 v53, v53, v54
	s_nop 0
	v_readlane_b32 s2, v53, 63
	s_nop 1
	v_mov_b32_e32 v53, s2
	v_mul_f32_e32 v53, 0x3a800000, v53
	v_add_f32_e32 v53, 0x358637bd, v53
	v_rsq_f32_e32 v53, v53
	s_nop 0
	v_mul_f32_e32 v16, v16, v53
	v_mul_f32_e32 v17, v17, v53
	v_mul_f32_e32 v18, v18, v53
	v_mul_f32_e32 v19, v19, v53
	v_mul_f32_e32 v20, v20, v53
	v_mul_f32_e32 v21, v21, v53
	v_mul_f32_e32 v22, v22, v53
	v_mul_f32_e32 v23, v23, v53
	v_mul_f32_e32 v24, v24, v53
	v_mul_f32_e32 v25, v25, v53
	v_mul_f32_e32 v26, v26, v53
	v_mul_f32_e32 v27, v27, v53
	v_mul_f32_e32 v28, v28, v53
	v_mul_f32_e32 v29, v29, v53
	v_mul_f32_e32 v30, v30, v53
	v_mul_f32_e32 v31, v31, v53
	v_mul_f32_e32 v16, v0, v16
	v_mul_f32_e32 v17, v1, v17
	v_mul_f32_e32 v18, v2, v18
	v_mul_f32_e32 v19, v3, v19
	v_mul_f32_e32 v20, v4, v20
	v_mul_f32_e32 v21, v5, v21
	v_mul_f32_e32 v22, v6, v22
	v_mul_f32_e32 v23, v7, v23
	v_mul_f32_e32 v24, v8, v24
	v_mul_f32_e32 v25, v9, v25
	v_mul_f32_e32 v26, v10, v26
	v_mul_f32_e32 v27, v11, v27
	v_mul_f32_e32 v28, v12, v28
	v_mul_f32_e32 v29, v13, v29
	v_mul_f32_e32 v30, v14, v30
	v_mul_f32_e32 v31, v15, v31
	v_cvt_pk_bf16_f32 v16, v16, v17
	v_cvt_pk_bf16_f32 v17, v18, v19
	v_cvt_pk_bf16_f32 v18, v20, v21
	v_cvt_pk_bf16_f32 v19, v22, v23
	v_cvt_pk_bf16_f32 v20, v24, v25
	v_cvt_pk_bf16_f32 v21, v26, v27
	v_cvt_pk_bf16_f32 v22, v28, v29
	v_cvt_pk_bf16_f32 v23, v30, v31
	s_lshl_b32 s24, s16, 11
	s_lshr_b32 s25, s16, 21
	s_add_u32 s24, s94, s24
	s_addc_u32 s25, s95, s25
	global_store_dwordx2 v55, v[16:17], s[24:25]
	global_store_dwordx2 v55, v[18:19], s[24:25] offset:512
	global_store_dwordx2 v55, v[20:21], s[24:25] offset:1024
	global_store_dwordx2 v55, v[22:23], s[24:25] offset:1536
	s_mov_b32 s16, s21
	s_cmp_lt_u32 s16, 0x10200
	s_cbranch_scc0 .LBB0_599
	s_add_u32 s21, s16, s34
	s_cmp_lt_u32 s21, 0x10200
	s_cbranch_scc0 .Lrms_n0_skip_b
	s_lshl_b32 s17, s21, 12
	s_lshr_b32 s20, s21, 20
	s_add_u32 s18, s92, s17
	s_addc_u32 s19, s93, s20
	global_load_dwordx4 v[16:19], v158, s[18:19]
	global_load_dwordx4 v[20:23], v158, s[18:19] offset:1024
	global_load_dwordx4 v[24:27], v158, s[18:19] offset:2048
	global_load_dwordx4 v[28:31], v158, s[18:19] offset:3072
	s_waitcnt vmcnt(4)
	s_branch .Lrms_n0_comp_b

.Lrms_n0_comp_b:
	v_pk_mul_f32 v[48:49], v[32:33], v[32:33]
	v_pk_mul_f32 v[50:51], v[34:35], v[34:35]
	v_pk_fma_f32 v[48:49], v[36:37], v[36:37], v[48:49]
	v_pk_fma_f32 v[50:51], v[38:39], v[38:39], v[50:51]
	v_pk_fma_f32 v[48:49], v[40:41], v[40:41], v[48:49]
	v_pk_fma_f32 v[50:51], v[42:43], v[42:43], v[50:51]
	v_pk_fma_f32 v[48:49], v[44:45], v[44:45], v[48:49]
	v_pk_fma_f32 v[50:51], v[46:47], v[46:47], v[50:51]
	s_nop 0
	v_pk_add_f32 v[48:49], v[48:49], v[50:51]
	s_nop 0
	v_add_f32_e32 v52, v48, v49
	s_nop 1
	v_add_f32_dpp v52, v52, v52 quad_perm:[1,0,3,2] row_mask:0xf bank_mask:0xf bound_ctrl:1
	s_nop 1
	v_add_f32_dpp v52, v52, v52 quad_perm:[2,3,0,1] row_mask:0xf bank_mask:0xf bound_ctrl:1
	s_nop 1
	v_add_f32_dpp v52, v52, v52 row_half_mirror row_mask:0xf bank_mask:0xf bound_ctrl:1
	s_nop 1
	v_add_f32_dpp v52, v52, v52 row_mirror row_mask:0xf bank_mask:0xf bound_ctrl:1
	s_nop 1
	v_mov_b32_dpp v53, v52 row_bcast:15 row_mask:0xa bank_mask:0xf
	v_add_f32_e32 v53, v52, v53
	s_nop 1
	v_mov_b32_dpp v54, v53 row_bcast:31 row_mask:0xc bank_mask:0xf
	v_add_f32_e32 v53, v53, v54
	s_nop 0
	v_readlane_b32 s2, v53, 63
	s_nop 1
	v_mov_b32_e32 v53, s2
	v_mul_f32_e32 v53, 0x3a800000, v53
	v_add_f32_e32 v53, 0x358637bd, v53
	v_rsq_f32_e32 v53, v53
	s_nop 0
	v_mul_f32_e32 v32, v32, v53
	v_mul_f32_e32 v33, v33, v53
	v_mul_f32_e32 v34, v34, v53
	v_mul_f32_e32 v35, v35, v53
	v_mul_f32_e32 v36, v36, v53
	v_mul_f32_e32 v37, v37, v53
	v_mul_f32_e32 v38, v38, v53
	v_mul_f32_e32 v39, v39, v53
	v_mul_f32_e32 v40, v40, v53
	v_mul_f32_e32 v41, v41, v53
	v_mul_f32_e32 v42, v42, v53
	v_mul_f32_e32 v43, v43, v53
	v_mul_f32_e32 v44, v44, v53
	v_mul_f32_e32 v45, v45, v53
	v_mul_f32_e32 v46, v46, v53
	v_mul_f32_e32 v47, v47, v53
	v_mul_f32_e32 v32, v0, v32
	v_mul_f32_e32 v33, v1, v33
	v_mul_f32_e32 v34, v2, v34
	v_mul_f32_e32 v35, v3, v35
	v_mul_f32_e32 v36, v4, v36
	v_mul_f32_e32 v37, v5, v37
	v_mul_f32_e32 v38, v6, v38
	v_mul_f32_e32 v39, v7, v39
	v_mul_f32_e32 v40, v8, v40
	v_mul_f32_e32 v41, v9, v41
	v_mul_f32_e32 v42, v10, v42
	v_mul_f32_e32 v43, v11, v43
	v_mul_f32_e32 v44, v12, v44
	v_mul_f32_e32 v45, v13, v45
	v_mul_f32_e32 v46, v14, v46
	v_mul_f32_e32 v47, v15, v47
	v_cvt_pk_bf16_f32 v32, v32, v33
	v_cvt_pk_bf16_f32 v33, v34, v35
	v_cvt_pk_bf16_f32 v34, v36, v37
	v_cvt_pk_bf16_f32 v35, v38, v39
	v_cvt_pk_bf16_f32 v36, v40, v41
	v_cvt_pk_bf16_f32 v37, v42, v43
	v_cvt_pk_bf16_f32 v38, v44, v45
	v_cvt_pk_bf16_f32 v39, v46, v47
	s_lshl_b32 s24, s16, 11
	s_lshr_b32 s25, s16, 21
	s_add_u32 s24, s94, s24
	s_addc_u32 s25, s95, s25
	global_store_dwordx2 v55, v[32:33], s[24:25]
	global_store_dwordx2 v55, v[34:35], s[24:25] offset:512
	global_store_dwordx2 v55, v[36:37], s[24:25] offset:1024
	global_store_dwordx2 v55, v[38:39], s[24:25] offset:1536
	s_mov_b32 s16, s21
	s_cmp_lt_u32 s16, 0x10200
	s_cbranch_scc0 .LBB0_599
	s_branch .Lrms_n0_loop

.LBB0_1058:
	s_or_b64 exec, exec, s[2:3]
	s_barrier
	s_mov_b64 s[2:3], exec
	v_readlane_b32 s4, v252, 24
	v_readlane_b32 s5, v252, 25
	s_and_b64 s[4:5], s[2:3], s[4:5]
	s_mov_b64 exec, s[4:5]
	s_cbranch_execz .LBB0_1061
	s_waitcnt vmcnt(0)
	v_readlane_b32 s80, v252, 6
	v_readlane_b32 s81, v252, 7
	v_readfirstlane_b32 s72, v152
	s_nop 4
	s_add_u32 s80, s80, 0x1000
	s_addc_u32 s81, s81, 0
	global_load_dwordx4 v[0:3], v158, s[80:81]
	global_load_dwordx4 v[4:7], v158, s[80:81] offset:1024
	global_load_dwordx4 v[8:11], v158, s[80:81] offset:2048
	global_load_dwordx4 v[12:15], v158, s[80:81] offset:3072
	v_lshrrev_b32_e32 v55, 1, v158
	v_mov_b32_e32 v159, 0
	s_lshl_b32 s73, s72, 12
	s_lshr_b32 s76, s72, 20
	s_add_u32 s74, s92, s73
	s_addc_u32 s75, s93, s76
	global_load_dwordx4 v[16:19], v158, s[74:75]
	global_load_dwordx4 v[20:23], v158, s[74:75] offset:1024
	global_load_dwordx4 v[24:27], v158, s[74:75] offset:2048
	global_load_dwordx4 v[28:31], v158, s[74:75] offset:3072
.Lrms_n1_loop:
	s_add_u32 s77, s72, s34
	s_cmp_lt_u32 s77, 0x10200
	s_cbranch_scc0 .Lrms_n1_skip_a
	s_lshl_b32 s73, s77, 12
	s_lshr_b32 s76, s77, 20
	s_add_u32 s74, s92, s73
	s_addc_u32 s75, s93, s76
	global_load_dwordx4 v[32:35], v158, s[74:75]
	global_load_dwordx4 v[36:39], v158, s[74:75] offset:1024
	global_load_dwordx4 v[40:43], v158, s[74:75] offset:2048
	global_load_dwordx4 v[44:47], v158, s[74:75] offset:3072
	s_waitcnt vmcnt(4)
	s_branch .Lrms_n1_comp_a

.Lrms_n1_comp_a:
	v_pk_mul_f32 v[48:49], v[16:17], v[16:17]
	v_pk_mul_f32 v[50:51], v[18:19], v[18:19]
	v_pk_fma_f32 v[48:49], v[20:21], v[20:21], v[48:49]
	v_pk_fma_f32 v[50:51], v[22:23], v[22:23], v[50:51]
	v_pk_fma_f32 v[48:49], v[24:25], v[24:25], v[48:49]
	v_pk_fma_f32 v[50:51], v[26:27], v[26:27], v[50:51]
	v_pk_fma_f32 v[48:49], v[28:29], v[28:29], v[48:49]
	v_pk_fma_f32 v[50:51], v[30:31], v[30:31], v[50:51]
	s_nop 0
	v_pk_add_f32 v[48:49], v[48:49], v[50:51]
	s_nop 0
	v_add_f32_e32 v52, v48, v49
	s_nop 1
	v_add_f32_dpp v52, v52, v52 quad_perm:[1,0,3,2] row_mask:0xf bank_mask:0xf bound_ctrl:1
	s_nop 1
	v_add_f32_dpp v52, v52, v52 quad_perm:[2,3,0,1] row_mask:0xf bank_mask:0xf bound_ctrl:1
	s_nop 1
	v_add_f32_dpp v52, v52, v52 row_half_mirror row_mask:0xf bank_mask:0xf bound_ctrl:1
	s_nop 1
	v_add_f32_dpp v52, v52, v52 row_mirror row_mask:0xf bank_mask:0xf bound_ctrl:1
	s_nop 1
	v_mov_b32_dpp v53, v52 row_bcast:15 row_mask:0xa bank_mask:0xf
	v_add_f32_e32 v53, v52, v53
	s_nop 1
	v_mov_b32_dpp v54, v53 row_bcast:31 row_mask:0xc bank_mask:0xf
	v_add_f32_e32 v53, v53, v54
	s_nop 0
	v_readlane_b32 s4, v53, 63
	s_nop 1
	v_mov_b32_e32 v53, s4
	v_mul_f32_e32 v53, 0x3a800000, v53
	v_add_f32_e32 v53, 0x358637bd, v53
	v_rsq_f32_e32 v53, v53
	s_nop 0
	v_mul_f32_e32 v16, v16, v53
	v_mul_f32_e32 v17, v17, v53
	v_mul_f32_e32 v18, v18, v53
	v_mul_f32_e32 v19, v19, v53
	v_mul_f32_e32 v20, v20, v53
	v_mul_f32_e32 v21, v21, v53
	v_mul_f32_e32 v22, v22, v53
	v_mul_f32_e32 v23, v23, v53
	v_mul_f32_e32 v24, v24, v53
	v_mul_f32_e32 v25, v25, v53
	v_mul_f32_e32 v26, v26, v53
	v_mul_f32_e32 v27, v27, v53
	v_mul_f32_e32 v28, v28, v53
	v_mul_f32_e32 v29, v29, v53
	v_mul_f32_e32 v30, v30, v53
	v_mul_f32_e32 v31, v31, v53
	v_mul_f32_e32 v16, v0, v16
	v_mul_f32_e32 v17, v1, v17
	v_mul_f32_e32 v18, v2, v18
	v_mul_f32_e32 v19, v3, v19
	v_mul_f32_e32 v20, v4, v20
	v_mul_f32_e32 v21, v5, v21
	v_mul_f32_e32 v22, v6, v22
	v_mul_f32_e32 v23, v7, v23
	v_mul_f32_e32 v24, v8, v24
	v_mul_f32_e32 v25, v9, v25
	v_mul_f32_e32 v26, v10, v26
	v_mul_f32_e32 v27, v11, v27
	v_mul_f32_e32 v28, v12, v28
	v_mul_f32_e32 v29, v13, v29
	v_mul_f32_e32 v30, v14, v30
	v_mul_f32_e32 v31, v15, v31
	v_cvt_pk_bf16_f32 v16, v16, v17
	v_cvt_pk_bf16_f32 v17, v18, v19
	v_cvt_pk_bf16_f32 v18, v20, v21
	v_cvt_pk_bf16_f32 v19, v22, v23
	v_cvt_pk_bf16_f32 v20, v24, v25
	v_cvt_pk_bf16_f32 v21, v26, v27
	v_cvt_pk_bf16_f32 v22, v28, v29
	v_cvt_pk_bf16_f32 v23, v30, v31
	s_lshl_b32 s78, s72, 11
	s_lshr_b32 s79, s72, 21
	s_add_u32 s78, s94, s78
	s_addc_u32 s79, s95, s79
	global_store_dwordx2 v55, v[16:17], s[78:79]
	global_store_dwordx2 v55, v[18:19], s[78:79] offset:512
	global_store_dwordx2 v55, v[20:21], s[78:79] offset:1024
	global_store_dwordx2 v55, v[22:23], s[78:79] offset:1536
	s_mov_b32 s72, s77
	s_cmp_lt_u32 s72, 0x10200
	s_cbranch_scc0 .LBB0_1061
	s_add_u32 s77, s72, s34
	s_cmp_lt_u32 s77, 0x10200
	s_cbranch_scc0 .Lrms_n1_skip_b
	s_lshl_b32 s73, s77, 12
	s_lshr_b32 s76, s77, 20
	s_add_u32 s74, s92, s73
	s_addc_u32 s75, s93, s76
	global_load_dwordx4 v[16:19], v158, s[74:75]
	global_load_dwordx4 v[20:23], v158, s[74:75] offset:1024
	global_load_dwordx4 v[24:27], v158, s[74:75] offset:2048
	global_load_dwordx4 v[28:31], v158, s[74:75] offset:3072
	s_waitcnt vmcnt(4)
	s_branch .Lrms_n1_comp_b

.Lrms_n1_comp_b:
	v_pk_mul_f32 v[48:49], v[32:33], v[32:33]
	v_pk_mul_f32 v[50:51], v[34:35], v[34:35]
	v_pk_fma_f32 v[48:49], v[36:37], v[36:37], v[48:49]
	v_pk_fma_f32 v[50:51], v[38:39], v[38:39], v[50:51]
	v_pk_fma_f32 v[48:49], v[40:41], v[40:41], v[48:49]
	v_pk_fma_f32 v[50:51], v[42:43], v[42:43], v[50:51]
	v_pk_fma_f32 v[48:49], v[44:45], v[44:45], v[48:49]
	v_pk_fma_f32 v[50:51], v[46:47], v[46:47], v[50:51]
	s_nop 0
	v_pk_add_f32 v[48:49], v[48:49], v[50:51]
	s_nop 0
	v_add_f32_e32 v52, v48, v49
	s_nop 1
	v_add_f32_dpp v52, v52, v52 quad_perm:[1,0,3,2] row_mask:0xf bank_mask:0xf bound_ctrl:1
	s_nop 1
	v_add_f32_dpp v52, v52, v52 quad_perm:[2,3,0,1] row_mask:0xf bank_mask:0xf bound_ctrl:1
	s_nop 1
	v_add_f32_dpp v52, v52, v52 row_half_mirror row_mask:0xf bank_mask:0xf bound_ctrl:1
	s_nop 1
	v_add_f32_dpp v52, v52, v52 row_mirror row_mask:0xf bank_mask:0xf bound_ctrl:1
	s_nop 1
	v_mov_b32_dpp v53, v52 row_bcast:15 row_mask:0xa bank_mask:0xf
	v_add_f32_e32 v53, v52, v53
	s_nop 1
	v_mov_b32_dpp v54, v53 row_bcast:31 row_mask:0xc bank_mask:0xf
	v_add_f32_e32 v53, v53, v54
	s_nop 0
	v_readlane_b32 s4, v53, 63
	s_nop 1
	v_mov_b32_e32 v53, s4
	v_mul_f32_e32 v53, 0x3a800000, v53
	v_add_f32_e32 v53, 0x358637bd, v53
	v_rsq_f32_e32 v53, v53
	s_nop 0
	v_mul_f32_e32 v32, v32, v53
	v_mul_f32_e32 v33, v33, v53
	v_mul_f32_e32 v34, v34, v53
	v_mul_f32_e32 v35, v35, v53
	v_mul_f32_e32 v36, v36, v53
	v_mul_f32_e32 v37, v37, v53
	v_mul_f32_e32 v38, v38, v53
	v_mul_f32_e32 v39, v39, v53
	v_mul_f32_e32 v40, v40, v53
	v_mul_f32_e32 v41, v41, v53
	v_mul_f32_e32 v42, v42, v53
	v_mul_f32_e32 v43, v43, v53
	v_mul_f32_e32 v44, v44, v53
	v_mul_f32_e32 v45, v45, v53
	v_mul_f32_e32 v46, v46, v53
	v_mul_f32_e32 v47, v47, v53
	v_mul_f32_e32 v32, v0, v32
	v_mul_f32_e32 v33, v1, v33
	v_mul_f32_e32 v34, v2, v34
	v_mul_f32_e32 v35, v3, v35
	v_mul_f32_e32 v36, v4, v36
	v_mul_f32_e32 v37, v5, v37
	v_mul_f32_e32 v38, v6, v38
	v_mul_f32_e32 v39, v7, v39
	v_mul_f32_e32 v40, v8, v40
	v_mul_f32_e32 v41, v9, v41
	v_mul_f32_e32 v42, v10, v42
	v_mul_f32_e32 v43, v11, v43
	v_mul_f32_e32 v44, v12, v44
	v_mul_f32_e32 v45, v13, v45
	v_mul_f32_e32 v46, v14, v46
	v_mul_f32_e32 v47, v15, v47
	v_cvt_pk_bf16_f32 v32, v32, v33
	v_cvt_pk_bf16_f32 v33, v34, v35
	v_cvt_pk_bf16_f32 v34, v36, v37
	v_cvt_pk_bf16_f32 v35, v38, v39
	v_cvt_pk_bf16_f32 v36, v40, v41
	v_cvt_pk_bf16_f32 v37, v42, v43
	v_cvt_pk_bf16_f32 v38, v44, v45
	v_cvt_pk_bf16_f32 v39, v46, v47
	s_lshl_b32 s78, s72, 11
	s_lshr_b32 s79, s72, 21
	s_add_u32 s78, s94, s78
	s_addc_u32 s79, s95, s79
	global_store_dwordx2 v55, v[32:33], s[78:79]
	global_store_dwordx2 v55, v[34:35], s[78:79] offset:512
	global_store_dwordx2 v55, v[36:37], s[78:79] offset:1024
	global_store_dwordx2 v55, v[38:39], s[78:79] offset:1536
	s_mov_b32 s72, s77
	s_cmp_lt_u32 s72, 0x10200
	s_cbranch_scc0 .LBB0_1061
	s_branch .Lrms_n1_loop
